# P3: 176 workgroups with 2 scan + 6 attention waves, 64 with 3+5; at most 3 attention units per wave
# speedup vs baseline: 1.0020x; 1.0020x over previous
; #define LAS __attribute__((address_space(3)))
; template <bool DRYS = false>
; __device__ __forceinline__ void scan_phase(const Args& a, int tid, int nthr, int blk, int nblk) {
;     u32x2* US64 = (u32x2*)((unsigned char*)a.out + Y_US); const f32x4* DEC = (const f32x4*)((const unsigned char*)a.out + Y_DEC);
;     const int per = (32768 + nblk - 1) / nblk;
;     if (tid >= nthr) return;
;     for (int q = tid; q < per; q += nthr) {
;     const int p = blk * per + q; if (p >= 32768) break;
;     const int hh = p >> 13, dv = (p >> 5) & 255, dq = p & 31; f32x4 st = (f32x4){0.f, 0.f, 0.f, 0.f};
;     u32x2* up = US64 + (size_t)hh * 8192 + dv * 32 + dq; const f32x4* dp = DEC + hh * 32 + dq;
; __global__ void __launch_bounds__(512) fwd_kernel(Args a) {
;     ...
;             LAS float* biasL = (LAS float*)(lds + 8 * 64 * VT_PITCH * 2);
;             for (int i = tid; i < 8 * 257; i += 512) biasL[i] = a.in[I_RELB][i] * 1.4426950408889634f;
;             __syncthreads();
;             if (wave >= 3) { LAS bf16_t* vT = (LAS bf16_t*)lds + wave * (64 * VT_PITCH);
;                 for (int u = (bx - 16) * 5 + (wave - 3); u < 4096; u += (G - 16) * 5) attn_unit<2, false>(a, u >> 4, u & 7, ((u >> 3) & 1) * 32, vT, biasL + (u & 7) * 257, lane); }
;             else scan_phase(a, tid, 192, bx - 16, G - 16);
.LBB0_560:
	global_load_dword v5, v[2:3], off
	v_add_u32_e32 v4, 0x200, v4
	v_cmp_lt_u32_e32 vcc, s3, v4
	v_lshl_add_u64 v[2:3], v[2:3], 0, s[6:7]
	s_or_b64 s[4:5], vcc, s[4:5]
	s_waitcnt vmcnt(0)
	v_mul_f32_e32 v5, 0x3fb8aa3b, v5
	ds_write_b32 v1, v5
	v_add_u32_e32 v1, 0x800, v1
	s_andn2_b64 exec, exec, s[4:5]
	s_cbranch_execnz .LBB0_560
	s_or_b64 exec, exec, s[4:5]
	s_mov_b64 s[4:5], -1
	s_movk_i32 s8, 0xc0
	s_cmp_lt_i32 s2, s8
	s_cselect_b32 s8, 0x80, s8
	s_cmp_lt_u32 s94, s8
	s_waitcnt lgkmcnt(0)
	s_barrier
	s_cbranch_scc0 .LBB0_571
	s_add_i32 s6, s58, -16
	s_abs_i32 s3, s6
	v_cvt_f32_u32_e32 v1, s3
	v_cmp_gt_u32_e32 vcc, s8, v178
	v_rcp_iflag_f32_e32 v1, v1
	s_nop 0
	v_mul_f32_e32 v1, 0x4f7ffffe, v1
	v_cvt_u32_f32_e32 v1, v1
	s_nop 0
	v_readfirstlane_b32 s7, v1
	s_and_saveexec_b64 s[4:5], vcc
	s_cbranch_execz .LBB0_570
	s_sub_i32 s10, 0, s3
	s_mul_i32 s10, s10, s7
	s_add_i32 s8, s58, 0x7fef
	s_mul_hi_u32 s10, s7, s10
	s_ashr_i32 s9, s8, 31
	s_abs_i32 s8, s8
	s_add_i32 s7, s7, s10
	s_ashr_i32 s6, s6, 31
	s_mul_hi_u32 s7, s8, s7
	s_xor_b32 s6, s9, s6
	s_mul_i32 s9, s7, s3
	s_sub_i32 s8, s8, s9
	s_add_i32 s9, s7, 1
	s_sub_i32 s10, s8, s3
	s_cmp_ge_u32 s8, s3
	s_cselect_b32 s7, s9, s7
	s_cselect_b32 s8, s10, s8
	s_add_i32 s9, s7, 1
	s_cmp_ge_u32 s8, s3
	s_cselect_b32 s3, s9, s7
	s_xor_b32 s3, s3, s6
	s_sub_i32 s26, s3, s6
	s_movk_i32 s26, 0xa0
	s_cmp_lt_i32 s2, 0xc0
	s_cselect_b32 s26, 0x80, s26
	v_cmp_gt_i32_e32 vcc, s26, v178
	s_and_b64 exec, exec, vcc
	s_cbranch_execz .LBB0_570
	s_add_i32 s3, s2, -16
	s_lshl_b32 s27, s3, 7
	s_cmp_lt_i32 s2, 0xc0
	s_cbranch_scc1 .Lp3_scanA
	s_add_i32 s3, s2, 0xffffff40
	s_mul_i32 s27, s3, 0xa0
	s_add_i32 s27, s27, 0x5800
.Lp3_scanA:
	v_add_u32_e32 v1, s27, v178
	v_and_b32_e32 v4, 31, v1
	s_add_u32 s6, s52, 0x4600000
	v_lshlrev_b32_e32 v3, 2, v4
	s_addc_u32 s7, s53, 0
	v_lshlrev_b32_e32 v2, 4, v4
	v_mov_b32_e32 v5, 0
	v_lshlrev_b32_e32 v6, 3, v4
	s_mov_b64 s[8:9], 0
	s_mov_b32 s28, 0x8000
	s_mov_b32 s29, 0xff00
	s_mov_b64 s[10:11], 0x4000
	s_mov_b64 s[14:15], 0x200000
	v_mov_b32_e32 v7, v178
	s_branch .LBB0_566

; #define LAS __attribute__((address_space(3)))
; __global__ void __launch_bounds__(512) fwd_kernel(Args a) {
;     ...
;             if (wave >= 3) { LAS bf16_t* vT = (LAS bf16_t*)lds + wave * (64 * VT_PITCH);
;                 for (int u = (bx - 16) * 5 + (wave - 3); u < 4096; u += (G - 16) * 5) attn_unit<2, false>(a, u >> 4, u & 7, ((u >> 3) & 1) * 32, vT, biasL + (u & 7) * 257, lane); }
.LBB0_571:
	s_andn2_b64 vcc, exec, s[4:5]
	s_cbranch_vccnz .LBB0_589
	s_movk_i32 s14, 0x5d
	s_cmp_lt_i32 s2, 0xc0
	s_cselect_b32 s3, 6, 5
	s_cselect_b32 s14, 0xffffff9e, s14
	s_mul_i32 s3, s2, s3
	s_add_i32 s3, s3, s93
	s_add_i32 s14, s3, s14
	s_cmpk_gt_i32 s14, 0xfff
	s_cbranch_scc1 .LBB0_589
	v_mov_b32_e32 v181, 0
	v_and_b32_e32 v180, 48, v178
	v_lshlrev_b32_e32 v3, 4, v178
	v_lshl_add_u64 v[4:5], s[54:55], 0, v[180:181]
	s_mov_b64 s[6:7], 0x3400000
	v_and_b32_e32 v180, 0x70, v3
	v_lshrrev_b32_e32 v1, 4, v176
	v_lshl_add_u64 v[182:183], v[4:5], 0, s[6:7]
	v_lshl_add_u64 v[4:5], s[54:55], 0, v[180:181]
	s_mov_b64 s[6:7], 0x4500000
	s_mul_i32 s3, s93, 0x2800
	v_lshlrev_b32_e32 v2, 3, v1
	v_lshl_add_u64 v[184:185], v[4:5], 0, s[6:7]
	v_lshlrev_b32_e32 v4, 2, v1
	v_bfe_u32 v1, v178, 2, 2
	s_add_i32 s3, s3, 0
	v_or_b32_e32 v1, v4, v1
	v_and_b32_e32 v0, 12, v0
	v_lshl_add_u32 v0, v0, 1, s3
	v_mul_u32_u24_e32 v1, 0xa0, v1
	v_add_u32_e32 v204, v0, v1
	v_mbcnt_lo_u32_b32 v0, -1, 0
	v_and_b32_e32 v177, 15, v178
	v_lshrrev_b32_e32 v179, 3, v176
	v_mbcnt_hi_u32_b32 v205, -1, v0
	s_add_u32 s15, s54, 0x2300000
	v_add_u32_e32 v3, s3, v180
	v_mul_u32_u24_e32 v5, 0xa0, v179
	s_movk_i32 s21, 0x560
	v_sub_u32_e32 v6, v177, v4
	s_movk_i32 s25, 0x1580
	v_and_b32_e32 v0, 64, v205
	s_mov_b32 s5, 0
	s_addc_u32 s20, s55, 0
	v_add_u32_e32 v202, 0x1d0, v6
	s_lshl_b32 s24, s14, 2
	v_add_u32_e32 v203, v3, v5
	v_lshlrev_b32_e32 v186, 1, v2
	s_mov_b32 s26, 0xf149f2ca
	v_lshlrev_b32_e32 v180, 1, v4
	v_xor_b32_e32 v206, 16, v205
	v_add_u32_e32 v207, 64, v0
	v_xor_b32_e32 v208, 32, v205
	s_branch .LBB0_575
